# E55: P0 prompt-row sum of squares: six ds_bpermute round trips replaced by four v_add_f32_dpp steps plus readlane combine in the same association (bit-identical), no LDS traffic; on E41
# baseline (speedup 1.0000x reference)
.Lp0_goA:
	v_pk_mul_f32 v[42:43], v[28:29], v[28:29]
	v_pk_mul_f32 v[44:45], v[26:27], v[26:27]
	v_pk_mul_f32 v[46:47], v[32:33], v[32:33]
	v_pk_mul_f32 v[48:49], v[30:31], v[30:31]
	v_pk_mov_b32 v[52:53], v[44:45], v[42:43] op_sel:[1,0]
	v_mov_b32_e32 v45, v43
	v_pk_mov_b32 v[42:43], v[48:49], v[46:47] op_sel:[1,0]
	v_mov_b32_e32 v49, v47
	v_mul_f32_e32 v2, v39, v39
	v_mul_f32_e32 v50, v41, v41
	v_pk_add_f32 v[44:45], v[52:53], v[44:45]
	v_pk_add_f32 v[42:43], v[42:43], v[48:49]
	v_mul_f32_e32 v54, v34, v34
	v_mul_f32_e32 v55, v35, v35
	v_mul_f32_e32 v56, v36, v36
	v_mul_f32_e32 v57, v37, v37
	v_pk_fma_f32 v[46:47], v[38:39], v[38:39], v[2:3] op_sel_hi:[1,1,0]
	v_pk_fma_f32 v[50:51], v[40:41], v[40:41], v[50:51] op_sel_hi:[1,1,0]
	v_pk_add_f32 v[44:45], v[44:45], v[44:45] op_sel:[0,1] op_sel_hi:[1,0]
	v_pk_add_f32 v[42:43], v[42:43], v[42:43] op_sel:[0,1] op_sel_hi:[1,0]
	v_mov_b32_e32 v47, v56
	v_mov_b32_e32 v51, v57
	v_mov_b32_e32 v45, v54
	v_mov_b32_e32 v43, v55
	v_pk_add_f32 v[46:47], v[46:47], v[50:51]
	v_pk_add_f32 v[42:43], v[44:45], v[42:43]
	s_nop 0
	v_pk_add_f32 v[42:43], v[42:43], v[46:47]
	s_nop 0
	v_add_f32_e32 v2, v42, v43
	s_nop 1
	v_add_f32_dpp v2, v2, v2 quad_perm:[1,0,3,2] row_mask:0xf bank_mask:0xf
	s_nop 1
	v_add_f32_dpp v2, v2, v2 quad_perm:[2,3,0,1] row_mask:0xf bank_mask:0xf
	s_nop 1
	v_add_f32_dpp v2, v2, v2 row_half_mirror row_mask:0xf bank_mask:0xf
	s_nop 1
	v_add_f32_dpp v2, v2, v2 row_mirror row_mask:0xf bank_mask:0xf
	s_nop 0
	v_readlane_b32 s0, v2, 0
	v_readlane_b32 s1, v2, 16
	v_readlane_b32 s99, v2, 32
	v_readlane_b32 s17, v2, 48
	v_mov_b32_e32 v42, s1
	v_add_f32_e32 v42, s0, v42
	v_mov_b32_e32 v43, s17
	v_add_f32_e32 v43, s99, v43
	v_add_f32_e32 v2, v42, v43
	v_fmamk_f32 v2, v2, 0x3a800000, v24
	v_mul_f32_e32 v42, 0x4f800000, v2
	v_cmp_gt_f32_e32 vcc, s7, v2
	s_nop 1
	v_cndmask_b32_e32 v2, v2, v42, vcc
	v_sqrt_f32_e32 v42, v2
	s_nop 0
	v_add_u32_e32 v43, -1, v42
	v_add_u32_e32 v44, 1, v42
	v_fma_f32 v45, -v43, v42, v2
	v_fma_f32 v46, -v44, v42, v2
	v_cmp_ge_f32_e64 s[0:1], 0, v45
	s_nop 1
	v_cndmask_b32_e64 v42, v42, v43, s[0:1]
	v_cmp_lt_f32_e64 s[0:1], 0, v46
	s_nop 1
	v_cndmask_b32_e64 v42, v42, v44, s[0:1]
	v_mul_f32_e32 v43, 0x37800000, v42
	v_cndmask_b32_e32 v42, v42, v43, vcc
	v_cmp_class_f32_e32 vcc, v2, v25
	s_nop 1
	v_cndmask_b32_e32 v2, v42, v2, vcc
	v_div_scale_f32 v42, s[0:1], v2, v2, 1.0
	v_rcp_f32_e32 v43, v42
	v_div_scale_f32 v44, vcc, 1.0, v2, 1.0
	v_fma_f32 v45, -v42, v43, 1.0
	v_fmac_f32_e32 v43, v45, v43
	v_mul_f32_e32 v45, v44, v43
	v_fma_f32 v46, -v42, v45, v44
	v_fmac_f32_e32 v45, v46, v43
	v_fma_f32 v42, -v42, v45, v44
	v_div_fmas_f32 v42, v42, v43, v45
	v_div_fixup_f32 v2, v42, v2, 1.0
	v_pk_mul_f32 v[26:27], v[26:27], v[2:3] op_sel_hi:[1,0]
	v_pk_mul_f32 v[28:29], v[28:29], v[2:3] op_sel_hi:[1,0]
	v_pk_mul_f32 v[30:31], v[30:31], v[2:3] op_sel_hi:[1,0]
	v_pk_mul_f32 v[32:33], v[32:33], v[2:3] op_sel_hi:[1,0]
	v_pk_mul_f32 v[38:39], v[38:39], v[2:3] op_sel_hi:[1,0]
	v_pk_mul_f32 v[40:41], v[40:41], v[2:3] op_sel_hi:[1,0]
	v_pk_mul_f32 v[34:35], v[34:35], v[2:3] op_sel_hi:[1,0]
	v_pk_mul_f32 v[36:37], v[36:37], v[2:3] op_sel_hi:[1,0]
	v_cvt_pk_bf16_f32 v26, v26, v27
	v_cvt_pk_bf16_f32 v27, v28, v29
	v_cvt_pk_bf16_f32 v28, v30, v31
	v_cvt_pk_bf16_f32 v29, v32, v33
	v_cvt_pk_bf16_f32 v30, v38, v39
	v_cvt_pk_bf16_f32 v31, v40, v41
	v_cvt_pk_bf16_f32 v32, v34, v35
	v_cvt_pk_bf16_f32 v33, v36, v37
	global_store_dwordx2 v[12:13], v[26:27], off
	global_store_dwordx2 v[12:13], v[28:29], off offset:512
	global_store_dwordx2 v[12:13], v[30:31], off offset:1024
	global_store_dwordx2 v[12:13], v[32:33], off offset:1536
	s_mov_b32 s98, 1
	s_branch .LBB0_89

.Lp0_goB:
	v_pk_mul_f32 v[42:43], v[170:171], v[170:171]
	v_pk_mul_f32 v[44:45], v[168:169], v[168:169]
	v_pk_mul_f32 v[46:47], v[174:175], v[174:175]
	v_pk_mul_f32 v[48:49], v[172:173], v[172:173]
	v_pk_mov_b32 v[52:53], v[44:45], v[42:43] op_sel:[1,0]
	v_mov_b32_e32 v45, v43
	v_pk_mov_b32 v[42:43], v[48:49], v[46:47] op_sel:[1,0]
	v_mov_b32_e32 v49, v47
	v_mul_f32_e32 v2, v181, v181
	v_mul_f32_e32 v50, v183, v183
	v_pk_add_f32 v[44:45], v[52:53], v[44:45]
	v_pk_add_f32 v[42:43], v[42:43], v[48:49]
	v_mul_f32_e32 v54, v176, v176
	v_mul_f32_e32 v55, v177, v177
	v_mul_f32_e32 v56, v178, v178
	v_mul_f32_e32 v57, v179, v179
	v_pk_fma_f32 v[46:47], v[180:181], v[180:181], v[2:3] op_sel_hi:[1,1,0]
	v_pk_fma_f32 v[50:51], v[182:183], v[182:183], v[50:51] op_sel_hi:[1,1,0]
	v_pk_add_f32 v[44:45], v[44:45], v[44:45] op_sel:[0,1] op_sel_hi:[1,0]
	v_pk_add_f32 v[42:43], v[42:43], v[42:43] op_sel:[0,1] op_sel_hi:[1,0]
	v_mov_b32_e32 v47, v56
	v_mov_b32_e32 v51, v57
	v_mov_b32_e32 v45, v54
	v_mov_b32_e32 v43, v55
	v_pk_add_f32 v[46:47], v[46:47], v[50:51]
	v_pk_add_f32 v[42:43], v[44:45], v[42:43]
	s_nop 0
	v_pk_add_f32 v[42:43], v[42:43], v[46:47]
	s_nop 0
	v_add_f32_e32 v2, v42, v43
	s_nop 1
	v_add_f32_dpp v2, v2, v2 quad_perm:[1,0,3,2] row_mask:0xf bank_mask:0xf
	s_nop 1
	v_add_f32_dpp v2, v2, v2 quad_perm:[2,3,0,1] row_mask:0xf bank_mask:0xf
	s_nop 1
	v_add_f32_dpp v2, v2, v2 row_half_mirror row_mask:0xf bank_mask:0xf
	s_nop 1
	v_add_f32_dpp v2, v2, v2 row_mirror row_mask:0xf bank_mask:0xf
	s_nop 0
	v_readlane_b32 s0, v2, 0
	v_readlane_b32 s1, v2, 16
	v_readlane_b32 s99, v2, 32
	v_readlane_b32 s17, v2, 48
	v_mov_b32_e32 v42, s1
	v_add_f32_e32 v42, s0, v42
	v_mov_b32_e32 v43, s17
	v_add_f32_e32 v43, s99, v43
	v_add_f32_e32 v2, v42, v43
	v_fmamk_f32 v2, v2, 0x3a800000, v24
	v_mul_f32_e32 v42, 0x4f800000, v2
	v_cmp_gt_f32_e32 vcc, s7, v2
	s_nop 1
	v_cndmask_b32_e32 v2, v2, v42, vcc
	v_sqrt_f32_e32 v42, v2
	s_nop 0
	v_add_u32_e32 v43, -1, v42
	v_add_u32_e32 v44, 1, v42
	v_fma_f32 v45, -v43, v42, v2
	v_fma_f32 v46, -v44, v42, v2
	v_cmp_ge_f32_e64 s[0:1], 0, v45
	s_nop 1
	v_cndmask_b32_e64 v42, v42, v43, s[0:1]
	v_cmp_lt_f32_e64 s[0:1], 0, v46
	s_nop 1
	v_cndmask_b32_e64 v42, v42, v44, s[0:1]
	v_mul_f32_e32 v43, 0x37800000, v42
	v_cndmask_b32_e32 v42, v42, v43, vcc
	v_cmp_class_f32_e32 vcc, v2, v25
	s_nop 1
	v_cndmask_b32_e32 v2, v42, v2, vcc
	v_div_scale_f32 v42, s[0:1], v2, v2, 1.0
	v_rcp_f32_e32 v43, v42
	v_div_scale_f32 v44, vcc, 1.0, v2, 1.0
	v_fma_f32 v45, -v42, v43, 1.0
	v_fmac_f32_e32 v43, v45, v43
	v_mul_f32_e32 v45, v44, v43
	v_fma_f32 v46, -v42, v45, v44
	v_fmac_f32_e32 v45, v46, v43
	v_fma_f32 v42, -v42, v45, v44
	v_div_fmas_f32 v42, v42, v43, v45
	v_div_fixup_f32 v2, v42, v2, 1.0
	v_pk_mul_f32 v[168:169], v[168:169], v[2:3] op_sel_hi:[1,0]
	v_pk_mul_f32 v[170:171], v[170:171], v[2:3] op_sel_hi:[1,0]
	v_pk_mul_f32 v[172:173], v[172:173], v[2:3] op_sel_hi:[1,0]
	v_pk_mul_f32 v[174:175], v[174:175], v[2:3] op_sel_hi:[1,0]
	v_pk_mul_f32 v[180:181], v[180:181], v[2:3] op_sel_hi:[1,0]
	v_pk_mul_f32 v[182:183], v[182:183], v[2:3] op_sel_hi:[1,0]
	v_pk_mul_f32 v[176:177], v[176:177], v[2:3] op_sel_hi:[1,0]
	v_pk_mul_f32 v[178:179], v[178:179], v[2:3] op_sel_hi:[1,0]
	v_cvt_pk_bf16_f32 v168, v168, v169
	v_cvt_pk_bf16_f32 v169, v170, v171
	v_cvt_pk_bf16_f32 v170, v172, v173
	v_cvt_pk_bf16_f32 v171, v174, v175
	v_cvt_pk_bf16_f32 v172, v180, v181
	v_cvt_pk_bf16_f32 v173, v182, v183
	v_cvt_pk_bf16_f32 v174, v176, v177
	v_cvt_pk_bf16_f32 v175, v178, v179
	global_store_dwordx2 v[12:13], v[168:169], off
	global_store_dwordx2 v[12:13], v[170:171], off offset:512
	global_store_dwordx2 v[12:13], v[172:173], off offset:1024
	global_store_dwordx2 v[12:13], v[174:175], off offset:1536
	s_mov_b32 s98, 0
	s_branch .LBB0_89
